# v84 + layer-0 pool-elementwise items in panel order (consecutive row blocks per workgroup share halo rows; context item last)
# speedup vs baseline: 1.0038x; 1.0038x over previous
; __global__ void __launch_bounds__(NWAVES * 64, 2) fwd_kernel(Args args) {
;     ...
;                 const int nitems = (nrows / 64) * 4;
;                 f32x4 pv[10]; float rreg;
;     ...
;                 { const int it0_ = bx < nitems ? bx : 0; PL_PREFETCH(it0_); }
;                 for (int it = bx; it < nitems; it += G) {
.LBB0_1174:
	s_andn2_b64 vcc, exec, s[0:1]
	s_movk_i32 s30, 0x1fff
	s_movk_i32 s44, 0xff00
	s_cbranch_vccnz .LBB0_1372
	v_readlane_b32 s0, v255, 8
	v_readlane_b32 s1, v255, 9
	s_mov_b32 s2, s0
	s_cmp_lg_u32 s0, 0
	s_cselect_b64 s[0:1], -1, 0
	s_cmp_eq_u32 s2, 0
	s_movk_i32 s2, 0x420
	s_cselect_b32 s4, s2, 0x400
	s_waitcnt vmcnt(0)
	v_mov_b32_e32 v42, v215
	s_mov_b32 s23, s84
	s_mov_b32 s5, s82
	s_and_b32 s100, s84, 7
	s_lshl_b32 s100, s100, 3
	s_bfe_u32 s101, s84, 0x30003
	s_add_i32 s100, s100, s101
	s_lshl_b32 s100, s100, 4
	s_lshr_b32 s101, s84, 6
	s_add_i32 s23, s100, s101
	s_mov_b32 s5, 4
	s_add_i32 s101, s84, 0x400
	s_add_i32 s8, s23, 16
	s_movk_i32 s100, 0x7fff
	s_cmpk_eq_u32 s4, 0x400
	s_cselect_b32 s101, s100, s101
	s_cselect_b32 s4, s8, s4
	s_mov_b32 s100, 0

; #define PL_DECODE(it_, g_, t0_, ss_, Ls_, b_) const int g_ = (it_) & 3, t0_ = ((it_) >> 2) * 64; int ss_, Ls_, b_; \
;         if (t0_ < MLAT) { ss_ = t0_ & ~(SEQ - 1); Ls_ = SEQ; b_ = t0_ >> 13; } else { ss_ = MLAT + ((t0_ - MLAT) & ~(CTXL - 1)); Ls_ = CTXL; b_ = 2; }
; __global__ void __launch_bounds__(NWAVES * 64, 2) fwd_kernel(Args args) {
;     ...
;                 for (int it = bx; it < nitems; it += G) {
;                     PL_DECODE(it, g, t0, seq_start, Ls, b) const int hw = 1 << g, T0 = t0 - seq_start;
;                     if (tid < 80) rs[tid] = rreg;
; #pragma unroll
;                     for (int k = 0; k < 10; ++k) tile[tid + 512 * k] = pv[k];
;                     __syncthreads();
;                     { const int itn_ = it + G < nitems ? it + G : it; PL_PREFETCH(itn_); }
.LBB0_1228:
	s_or_b64 exec, exec, s[6:7]
	s_add_i32 s21, s23, s5
	s_add_i32 s100, s100, 1
	s_cmp_eq_u32 s100, 4
	s_cselect_b32 s21, s101, s21
	s_cmp_gt_u32 s100, 4
	s_cselect_b32 s21, 0x7fff, s21
	s_lshl_b32 s20, s21, 4
	s_sub_i32 s20, s20, s19
	s_cmp_ge_i32 s21, s4
	s_cselect_b64 s[6:7], -1, 0
	s_cmp_lt_i32 s21, s4
	s_cselect_b32 s8, s21, s23
	s_lshl_b32 s14, s8, 4
	s_and_b32 s31, s14, 0xffffffc0
	s_cmpk_lt_i32 s31, 0x4000
	s_cselect_b32 s15, 0xffffe000, s44
	s_cselect_b32 s33, s30, 0xff
	s_and_b32 s36, s15, s14
	s_sub_i32 s34, s31, s36
	s_add_i32 s37, s34, -8
	v_add_u32_e32 v129, s37, v65
	ds_write_b128 v66, v[36:39] offset:512
	ds_write_b128 v66, v[32:35] offset:8704
	ds_write_b128 v66, v[28:31] offset:16896
	ds_write_b128 v66, v[24:27] offset:25088
	ds_write_b128 v66, v[20:23] offset:33280
	ds_write_b128 v66, v[16:19] offset:41472
	ds_write_b128 v66, v[12:15] offset:49664
	ds_write_b128 v66, v[8:11] offset:57856
	ds_write_b128 v88, v[4:7]
	ds_write_b128 v89, v[0:3]
	v_min_i32_e32 v0, s33, v129
	v_cmp_lt_i32_e32 vcc, -1, v129
	s_lshl_b32 s8, s8, 8
	s_and_b32 s35, s8, 0x300
	v_cndmask_b32_e32 v130, 0, v0, vcc
	v_add_u32_e32 v0, s36, v130
	s_mov_b64 s[14:15], -1
	s_and_b64 vcc, exec, s[0:1]
	v_ashrrev_i32_e32 v1, 31, v0
	s_waitcnt lgkmcnt(0)
	s_barrier
	s_cbranch_vccz .LBB0_1230
	s_load_dwordx2 s[14:15], s[2:3], 0xb8
	v_lshlrev_b64 v[2:3], 11, v[0:1]
	s_lshl_b32 s8, s35, 1
	v_mov_b32_e32 v61, v213
	s_waitcnt lgkmcnt(0)
	v_lshl_add_u64 v[2:3], s[14:15], 0, v[2:3]
	v_lshl_add_u64 v[2:3], v[2:3], 0, s[8:9]
	v_lshl_add_u64 v[2:3], v[2:3], 0, v[60:61]
	v_add_co_u32_e32 v2, vcc, 0x14200000, v2
	s_mov_b64 s[14:15], 0
	s_nop 0
	v_addc_co_u32_e32 v3, vcc, 0, v3, vcc
	global_load_dwordx2 v[2:3], v[2:3], off
	s_waitcnt vmcnt(0)
	v_lshlrev_b32_e32 v36, 16, v2
	v_and_b32_e32 v37, 0xffff0000, v2
	v_lshlrev_b32_e32 v38, 16, v3
	v_and_b32_e32 v39, 0xffff0000, v3
